# MLA QK phase: all 8-byte instructions on 8-byte boundaries (s_waitcnt paired with a 4-byte v_exp, 8-byte filler between the MFMA pair), streamlined staging, loop heads aligned to 64 bytes
# speedup vs baseline: 1.0016x; 1.0016x over previous
; #define LAS __attribute__((address_space(3)))
; #define ATT_BAR() asm volatile("s_waitcnt lgkmcnt(0)\n\ts_barrier" ::: "memory")
; template <int DQK> __device__ __forceinline__ void x1_tile(LAS unsigned char* lds, const bf16x8 (&qf)[2][DQK / 32], const float (&m)[2], f32x4 (&s)[2][4], int fr, int fq) {
;     constexpr int NKS = DQK / 32;
; #pragma unroll
;     for (int q = 0; q < 2; ++q) { const float c = (m[q] > -1e29f) ? -m[q] : 0.f;
; #pragma unroll
;         for (int ss = 0; ss < 4; ++ss) s[q][ss] = (f32x4){c, c, c, c}; }
; #pragma unroll
;     for (int ss = 0; ss < 4; ++ss)
; #pragma unroll
;         for (int ks = 0; ks < NKS; ++ks) {
;             const bf16x8 kf = *(const LAS bf16x8*)(lds + k_off<DQK>(16 * ss + fr, 4 * ks + fq));
; #pragma unroll
;             for (int q = 0; q < 2; ++q) s[q][ss] = __builtin_amdgcn_mfma_f32_16x16x32_bf16(kf, qf[q][ks], s[q][ss], 0, 0, 0);
;         }
; }
; template <int DQK> __device__ __forceinline__ void causal_pass_pipe(LAS unsigned char* lds, const bf16* K0, int p0, const bf16* K1, int p1, const bf16* V, int pv, int thi,
;         const bf16x8 (&qf)[2][DQK / 32], const int (&tpos)[2], int wave_tmin, int wave_tmax, f32x4 (&o)[2][4], int tid) {
;     ...
;     float m[2] = {NEG, NEG}, l[2] = {0.f, 0.f};
; #pragma unroll
;     for (int i = 0; i < 2; ++i)
; #pragma unroll
;         for (int dt = 0; dt < 4; ++dt) o[i][dt] = (f32x4){0.f, 0.f, 0.f, 0.f};
;     Stage<DQK> st;
;     {
;         Stage<DQK> st1;
;         stage_load<DQK>(st, K0, p0, K1, p1, V, pv, 0, true, tid);
;         if (thi >= 1) stage_load<DQK>(st1, K0, p0, K1, p1, V, pv, 1, true, tid);
;         stage_store<DQK>(st, lds, true, tid);
;         if (thi >= 1) stage_store<DQK>(st1, lds + SLOT, true, tid);
;     }
;     ATT_BAR();
;     f32x4 sa[2][4], sb[2][4]; bool ca = true, cb = false;
;     x1_tile<DQK>(lds, qf, m, sa, fr, fq);
;     if (63 <= wave_tmin) x2_tile<true>(0, tpos, m, l, o, sa, fq); else x2_tile<false>(0, tpos, m, l, o, sa, fq);
.Lmla_nok1_0:
	v_mov_b32_e32 v96, 0
	v_mov_b32_e32 v97, 0
	v_mov_b32_e32 v98, 0
	v_mov_b32_e32 v99, 0
	v_mov_b32_e32 v88, 0
	v_mov_b32_e32 v89, 0
	v_mov_b32_e32 v90, 0
	v_mov_b32_e32 v91, 0
	v_mov_b32_e32 v92, 0
	v_mov_b32_e32 v93, 0
	v_mov_b32_e32 v94, 0
	v_mov_b32_e32 v95, 0
	v_mov_b32_e32 v48, 0
	v_mov_b32_e32 v49, 0
	v_mov_b32_e32 v50, 0
	v_mov_b32_e32 v51, 0
	v_mov_b32_e32 v165, 0
	v_mov_b32_e32 v200, v183
	v_mov_b32_e32 v84, 0
	v_mov_b32_e32 v85, 0
	v_mov_b32_e32 v86, 0
	v_mov_b32_e32 v87, 0
	v_mov_b32_e32 v76, 0
	v_mov_b32_e32 v77, 0
	v_mov_b32_e32 v78, 0
	v_mov_b32_e32 v79, 0
	v_mov_b32_e32 v80, 0
	v_mov_b32_e32 v81, 0
	v_mov_b32_e32 v82, 0
	v_mov_b32_e32 v83, 0
	v_mov_b32_e32 v56, 0
	v_mov_b32_e32 v57, 0
	v_mov_b32_e32 v58, 0
	v_mov_b32_e32 v59, 0
	v_mov_b32_e32 v164, 0
	v_mov_b32_e32 v211, v183
	s_mov_b32 s100, 0x20000
	s_mov_b32 s101, 0
	s_mov_b32 s98, 0x1000
	s_mov_b32 s99, 0
	v_cmp_lt_f32_e64 s[66:67], s77, v200
	v_cmp_lt_f32_e64 s[68:69], s77, v211
	s_nop 1
	v_cndmask_b32_e64 v197, 0, v200, s[66:67]
	v_cndmask_b32_e64 v198, 0, v211, s[68:69]
	s_and_b64 s[64:65], s[66:67], s[68:69]
	v_sub_f32_e32 v204, 0, v197
	v_mov_b32_e32 v205, v204
	v_mov_b32_e32 v206, v204
	v_mov_b32_e32 v207, v204
	v_sub_f32_e32 v252, 0, v198
	v_mov_b32_e32 v253, v252
	v_mov_b32_e32 v254, v252
	v_mov_b32_e32 v255, v252
	ds_read_b128 v[236:239], v199
	ds_read_b128 v[240:243], v201
	ds_read_b128 v[244:247], v210
	s_waitcnt lgkmcnt(0)
	v_mfma_f32_16x16x32_bf16 v[100:103], v[236:239], v[0:3], v[204:207]
	v_mfma_f32_16x16x32_bf16 v[116:119], v[236:239], v[12:15], v[252:255]
	v_mfma_f32_16x16x32_bf16 v[100:103], v[240:243], v[4:7], v[100:103]
	v_mfma_f32_16x16x32_bf16 v[116:119], v[240:243], v[16:19], v[116:119]
	v_mfma_f32_16x16x32_bf16 v[100:103], v[244:247], v[8:11], v[100:103]
	v_mfma_f32_16x16x32_bf16 v[116:119], v[244:247], v[20:23], v[116:119]
	ds_read_b128 v[236:239], v199 offset:4096
	ds_read_b128 v[240:243], v201 offset:4096
	ds_read_b128 v[244:247], v210 offset:4096
	s_waitcnt lgkmcnt(0)
	v_mfma_f32_16x16x32_bf16 v[104:107], v[236:239], v[0:3], v[204:207]
	v_mfma_f32_16x16x32_bf16 v[120:123], v[236:239], v[12:15], v[252:255]
	v_mfma_f32_16x16x32_bf16 v[104:107], v[240:243], v[4:7], v[104:107]
	v_mfma_f32_16x16x32_bf16 v[120:123], v[240:243], v[16:19], v[120:123]
	v_mfma_f32_16x16x32_bf16 v[104:107], v[244:247], v[8:11], v[104:107]
	v_mfma_f32_16x16x32_bf16 v[120:123], v[244:247], v[20:23], v[120:123]
	ds_read_b128 v[236:239], v199 offset:8192
	ds_read_b128 v[240:243], v201 offset:8192
	ds_read_b128 v[244:247], v210 offset:8192
	s_waitcnt lgkmcnt(0)
	v_mfma_f32_16x16x32_bf16 v[108:111], v[236:239], v[0:3], v[204:207]
	v_mfma_f32_16x16x32_bf16 v[124:127], v[236:239], v[12:15], v[252:255]
	v_mfma_f32_16x16x32_bf16 v[108:111], v[240:243], v[4:7], v[108:111]
	v_mfma_f32_16x16x32_bf16 v[124:127], v[240:243], v[16:19], v[124:127]
	v_mfma_f32_16x16x32_bf16 v[108:111], v[244:247], v[8:11], v[108:111]
	v_mfma_f32_16x16x32_bf16 v[124:127], v[244:247], v[20:23], v[124:127]
	ds_read_b128 v[236:239], v199 offset:12288
	ds_read_b128 v[240:243], v201 offset:12288
	ds_read_b128 v[244:247], v210 offset:12288
	s_waitcnt lgkmcnt(0)
	v_mfma_f32_16x16x32_bf16 v[112:115], v[236:239], v[0:3], v[204:207]
	v_mfma_f32_16x16x32_bf16 v[128:131], v[236:239], v[12:15], v[252:255]
	v_mfma_f32_16x16x32_bf16 v[112:115], v[240:243], v[4:7], v[112:115]
	v_mfma_f32_16x16x32_bf16 v[128:131], v[240:243], v[16:19], v[128:131]
	v_mfma_f32_16x16x32_bf16 v[112:115], v[244:247], v[8:11], v[112:115]
	v_mfma_f32_16x16x32_bf16 v[128:131], v[244:247], v[20:23], v[128:131]
	s_nop 7
	s_nop 7
	s_add_i32 s32, s49, 1
	s_cmp_eq_u32 s32, s9
	s_cbranch_scc1 .Lmla_mask5
	s_branch .Lmla_slow5_0
	.p2align 6

; #define LAS __attribute__((address_space(3)))
; template <int I0, int NQ, int VO> __device__ __forceinline__ void tile_y(LAS unsigned char* lds, float (&l)[2], f32x4 (&o)[2][4], f32x4 (&s)[2][4], int fr, int fq) {
;     bf16x8 pb[NQ][2];
; #pragma unroll
;     for (int q = 0; q < NQ; ++q) {
;         f32x4 (&sq)[4] = s[I0 + q];
;         f32x2_t rs2 = {0.f, 0.f};
; #pragma unroll
;         for (int ss = 0; ss < 4; ++ss) {
; #pragma unroll
;             for (int i = 0; i < 4; ++i) sq[ss][i] = __builtin_amdgcn_exp2f(sq[ss][i]);
;             rs2 += (f32x2_t){sq[ss][0], sq[ss][1]}; rs2 += (f32x2_t){sq[ss][2], sq[ss][3]};
;         }
;         l[I0 + q] += rs2.x + rs2.y;
; #pragma unroll
;         for (int j = 0; j < 2; ++j) {
;             const v4u w = (v4u){cvtpk(sq[2 * j][0], sq[2 * j][1]), cvtpk(sq[2 * j][2], sq[2 * j][3]), cvtpk(sq[2 * j + 1][0], sq[2 * j + 1][1]), cvtpk(sq[2 * j + 1][2], sq[2 * j + 1][3])};
;             pb[q][j] = __builtin_bit_cast(bf16x8, w);
;         }
;     }
; #pragma unroll
;     for (int dt = 0; dt < 4; ++dt)
; #pragma unroll
;         for (int j = 0; j < 2; ++j) {
;             LAS unsigned char* vp = lds + VO + ((32 * j + 4 * fq + (fr >> 2)) * VSTR + 16 * dt + 4 * (fr & 3)) * 2;
;             const s16x4 lo = __builtin_bit_cast(s16x4, __builtin_amdgcn_ds_read_tr16_b64_v4i16((LAS v4i16_t*)vp));
;             const s16x4 hi = __builtin_bit_cast(s16x4, __builtin_amdgcn_ds_read_tr16_b64_v4i16((LAS v4i16_t*)(vp + 16 * VSTR * 2)));
;             const bf16x8 vf = (bf16x8){lo[0], lo[1], lo[2], lo[3], hi[0], hi[1], hi[2], hi[3]};
; #pragma unroll
;             for (int q = 0; q < NQ; ++q) o[I0 + q][dt] = __builtin_amdgcn_mfma_f32_16x16x32_bf16(vf, pb[q][j], o[I0 + q][dt], 0, 0, 0);
;         }
; }
; template <int DQK> __device__ __forceinline__ void x1_tile(LAS unsigned char* lds, const bf16x8 (&qf)[2][DQK / 32], const float (&m)[2], f32x4 (&s)[2][4], int fr, int fq) {
;     constexpr int NKS = DQK / 32;
; #pragma unroll
;     for (int q = 0; q < 2; ++q) { const float c = (m[q] > -1e29f) ? -m[q] : 0.f;
; #pragma unroll
;         for (int ss = 0; ss < 4; ++ss) s[q][ss] = (f32x4){c, c, c, c}; }
; #pragma unroll
;     for (int ss = 0; ss < 4; ++ss)
; #pragma unroll
;         for (int ks = 0; ks < NKS; ++ks) {
;             const bf16x8 kf = *(const LAS bf16x8*)(lds + k_off<DQK>(16 * ss + fr, 4 * ks + fq));
; #pragma unroll
.Lmla_nostage0:
	s_cmp_ge_u32 s49, s9
	s_cbranch_scc1 .Lmla_tail0
	ds_read_b64_tr_b16 v[220:221], v251 offset:16384
	ds_read_b64_tr_b16 v[222:223], v251 offset:18944
	ds_read_b64_tr_b16 v[224:225], v251 offset:21504
	ds_read_b64_tr_b16 v[226:227], v251 offset:24064
	ds_read_b64_tr_b16 v[228:229], v251 offset:16416
	ds_read_b64_tr_b16 v[230:231], v251 offset:18976
	ds_read_b64_tr_b16 v[232:233], v251 offset:21536
	ds_read_b64_tr_b16 v[234:235], v251 offset:24096
	ds_read_b128 v[236:239], v195
	ds_read_b128 v[240:243], v196
	ds_read_b128 v[244:247], v202
	s_waitcnt lgkmcnt(2)
	v_exp_f32_e32 v100, v100
	v_mfma_f32_16x16x32_bf16 v[24:27], v[236:239], v[0:3], v[204:207]
	v_exp_f32_e64 v101, v101
	v_mfma_f32_16x16x32_bf16 v[40:43], v[236:239], v[12:15], v[252:255]
	ds_read_b128 v[236:239], v195 offset:4096
	s_waitcnt lgkmcnt(2)
	v_exp_f32_e32 v102, v102
	v_mfma_f32_16x16x32_bf16 v[24:27], v[240:243], v[4:7], v[24:27]
	v_exp_f32_e64 v103, v103
	v_mfma_f32_16x16x32_bf16 v[40:43], v[240:243], v[16:19], v[40:43]
	ds_read_b128 v[240:243], v196 offset:4096
	s_waitcnt lgkmcnt(2)
	v_exp_f32_e32 v104, v104
	v_mfma_f32_16x16x32_bf16 v[24:27], v[244:247], v[8:11], v[24:27]
	v_exp_f32_e64 v105, v105
	v_mfma_f32_16x16x32_bf16 v[40:43], v[244:247], v[20:23], v[40:43]
	ds_read_b128 v[244:247], v202 offset:4096
	s_waitcnt lgkmcnt(2)
	v_exp_f32_e32 v106, v106
	v_mfma_f32_16x16x32_bf16 v[28:31], v[236:239], v[0:3], v[204:207]
	v_exp_f32_e64 v107, v107
	v_mfma_f32_16x16x32_bf16 v[44:47], v[236:239], v[12:15], v[252:255]
	ds_read_b128 v[236:239], v195 offset:8192
	s_waitcnt lgkmcnt(2)
	v_exp_f32_e32 v108, v108
	v_mfma_f32_16x16x32_bf16 v[28:31], v[240:243], v[4:7], v[28:31]
	v_exp_f32_e64 v109, v109
	v_mfma_f32_16x16x32_bf16 v[44:47], v[240:243], v[16:19], v[44:47]
	ds_read_b128 v[240:243], v196 offset:8192
	s_waitcnt lgkmcnt(2)
	v_exp_f32_e32 v110, v110
	v_mfma_f32_16x16x32_bf16 v[28:31], v[244:247], v[8:11], v[28:31]
	v_exp_f32_e64 v111, v111
	v_mfma_f32_16x16x32_bf16 v[44:47], v[244:247], v[20:23], v[44:47]
	ds_read_b128 v[244:247], v202 offset:8192
	s_waitcnt lgkmcnt(2)
	v_exp_f32_e32 v112, v112
	v_mfma_f32_16x16x32_bf16 v[32:35], v[236:239], v[0:3], v[204:207]
	v_exp_f32_e64 v113, v113
	v_mfma_f32_16x16x32_bf16 v[212:215], v[236:239], v[12:15], v[252:255]
	ds_read_b128 v[236:239], v195 offset:12288
	s_waitcnt lgkmcnt(2)
	v_exp_f32_e32 v114, v114
	v_mfma_f32_16x16x32_bf16 v[32:35], v[240:243], v[4:7], v[32:35]
	v_exp_f32_e64 v115, v115
	v_mfma_f32_16x16x32_bf16 v[212:215], v[240:243], v[16:19], v[212:215]
	ds_read_b128 v[240:243], v196 offset:12288
	s_waitcnt lgkmcnt(2)
	v_exp_f32_e32 v116, v116
	v_mfma_f32_16x16x32_bf16 v[32:35], v[244:247], v[8:11], v[32:35]
	v_exp_f32_e64 v117, v117
	v_mfma_f32_16x16x32_bf16 v[212:215], v[244:247], v[20:23], v[212:215]
	ds_read_b128 v[244:247], v202 offset:12288
	s_waitcnt lgkmcnt(2)
	v_exp_f32_e32 v118, v118
	v_mfma_f32_16x16x32_bf16 v[36:39], v[236:239], v[0:3], v[204:207]
	v_exp_f32_e64 v119, v119
	v_mfma_f32_16x16x32_bf16 v[216:219], v[236:239], v[12:15], v[252:255]
	ds_read_b64_tr_b16 v[236:237], v251 offset:16448
	ds_read_b64_tr_b16 v[238:239], v251 offset:19008
	s_waitcnt lgkmcnt(3)
	v_exp_f32_e32 v120, v120
	v_mfma_f32_16x16x32_bf16 v[36:39], v[240:243], v[4:7], v[36:39]
	v_exp_f32_e64 v121, v121
	v_mfma_f32_16x16x32_bf16 v[216:219], v[240:243], v[16:19], v[216:219]
	ds_read_b64_tr_b16 v[240:241], v251 offset:21568
	ds_read_b64_tr_b16 v[242:243], v251 offset:24128
	s_waitcnt lgkmcnt(4)
	v_exp_f32_e32 v122, v122
	v_mfma_f32_16x16x32_bf16 v[36:39], v[244:247], v[8:11], v[36:39]
	v_exp_f32_e64 v123, v123
	v_mfma_f32_16x16x32_bf16 v[216:219], v[244:247], v[20:23], v[216:219]
	ds_read_b64_tr_b16 v[244:245], v251 offset:16480
	ds_read_b64_tr_b16 v[246:247], v251 offset:19040
	v_exp_f32_e32 v124, v124
	v_exp_f32_e32 v125, v125
	v_exp_f32_e32 v126, v126
	v_exp_f32_e32 v127, v127
	v_exp_f32_e32 v128, v128
	v_exp_f32_e32 v129, v129
	v_exp_f32_e32 v130, v130
	v_exp_f32_e32 v131, v131
	v_cvt_pk_bf16_f32 v132, v100, v101
	v_cvt_pk_bf16_f32 v133, v102, v103
	v_cvt_pk_bf16_f32 v134, v104, v105
	v_cvt_pk_bf16_f32 v135, v106, v107
	v_cvt_pk_bf16_f32 v136, v108, v109
	v_cvt_pk_bf16_f32 v137, v110, v111
	v_cvt_pk_bf16_f32 v138, v112, v113
	v_cvt_pk_bf16_f32 v139, v114, v115
	v_cvt_pk_bf16_f32 v140, v116, v117
	v_cvt_pk_bf16_f32 v141, v118, v119
	v_cvt_pk_bf16_f32 v142, v120, v121
	v_cvt_pk_bf16_f32 v143, v122, v123
	v_cvt_pk_bf16_f32 v52, v124, v125
	v_cvt_pk_bf16_f32 v53, v126, v127
	v_cvt_pk_bf16_f32 v54, v128, v129
	v_cvt_pk_bf16_f32 v55, v130, v131
	s_waitcnt lgkmcnt(15)
	s_nop 0
	v_mfma_f32_16x16x32_bf16 v[96:99], v[220:223], v[132:135], v[96:99]
	v_add_f32_e32 v100, v100, v101
	v_add_f32_e32 v102, v102, v103
	v_mfma_f32_16x16x32_bf16 v[84:87], v[220:223], v[140:143], v[84:87]
	v_add_f32_e32 v104, v104, v105
	v_add_f32_e32 v106, v106, v107
	v_mfma_f32_16x16x32_bf16 v[96:99], v[224:227], v[136:139], v[96:99]
	v_add_f32_e32 v108, v108, v109
	v_add_f32_e32 v110, v110, v111
	v_mfma_f32_16x16x32_bf16 v[84:87], v[224:227], v[52:55], v[84:87]
	v_add_f32_e32 v112, v112, v113
	v_add_f32_e32 v114, v114, v115
	ds_read_b64_tr_b16 v[220:221], v251 offset:21600
	ds_read_b64_tr_b16 v[222:223], v251 offset:24160
	v_mfma_f32_16x16x32_bf16 v[88:91], v[228:231], v[132:135], v[88:91]
	v_add_f32_e32 v100, v100, v102
	v_add_f32_e32 v104, v104, v106
	v_mfma_f32_16x16x32_bf16 v[76:79], v[228:231], v[140:143], v[76:79]
	v_add_f32_e32 v108, v108, v110
	v_add_f32_e32 v112, v112, v114
	v_mfma_f32_16x16x32_bf16 v[88:91], v[232:235], v[136:139], v[88:91]
	v_add_f32_e32 v100, v100, v104
	v_add_f32_e32 v108, v108, v112
	v_mfma_f32_16x16x32_bf16 v[76:79], v[232:235], v[52:55], v[76:79]
	v_add_f32_e32 v100, v100, v108
	v_add_f32_e32 v165, v165, v100
	s_waitcnt lgkmcnt(0)
	s_nop 0
	v_mfma_f32_16x16x32_bf16 v[92:95], v[236:239], v[132:135], v[92:95]
	v_add_f32_e32 v116, v116, v117
	v_add_f32_e32 v118, v118, v119
	v_mfma_f32_16x16x32_bf16 v[80:83], v[236:239], v[140:143], v[80:83]
	v_add_f32_e32 v120, v120, v121
	v_add_f32_e32 v122, v122, v123
	v_mfma_f32_16x16x32_bf16 v[92:95], v[240:243], v[136:139], v[92:95]
	v_add_f32_e32 v124, v124, v125
	v_add_f32_e32 v126, v126, v127
	v_mfma_f32_16x16x32_bf16 v[80:83], v[240:243], v[52:55], v[80:83]
	v_add_f32_e32 v128, v128, v129
	v_add_f32_e32 v130, v130, v131
	v_mfma_f32_16x16x32_bf16 v[48:51], v[244:247], v[132:135], v[48:51]
	v_add_f32_e32 v116, v116, v118
	v_add_f32_e32 v120, v120, v122
	v_mfma_f32_16x16x32_bf16 v[56:59], v[244:247], v[140:143], v[56:59]
	v_add_f32_e32 v124, v124, v126
	v_add_f32_e32 v128, v128, v130
	v_mfma_f32_16x16x32_bf16 v[48:51], v[220:223], v[136:139], v[48:51]
	v_add_f32_e32 v116, v116, v120
	v_add_f32_e32 v124, v124, v128
	v_mfma_f32_16x16x32_bf16 v[56:59], v[220:223], v[52:55], v[56:59]
	v_add_f32_e32 v116, v116, v124
	v_add_f32_e32 v164, v164, v116
	s_add_i32 s32, s49, 1
	s_cmp_eq_u32 s32, s9
	s_cbranch_scc1 .Lmla_mask0

; #define LAS __attribute__((address_space(3)))
; template <int I0, int NQ, int VO> __device__ __forceinline__ void tile_y(LAS unsigned char* lds, float (&l)[2], f32x4 (&o)[2][4], f32x4 (&s)[2][4], int fr, int fq) {
;     bf16x8 pb[NQ][2];
; #pragma unroll
;     for (int q = 0; q < NQ; ++q) {
;         f32x4 (&sq)[4] = s[I0 + q];
;         f32x2_t rs2 = {0.f, 0.f};
; #pragma unroll
;         for (int ss = 0; ss < 4; ++ss) {
; #pragma unroll
;             for (int i = 0; i < 4; ++i) sq[ss][i] = __builtin_amdgcn_exp2f(sq[ss][i]);
;             rs2 += (f32x2_t){sq[ss][0], sq[ss][1]}; rs2 += (f32x2_t){sq[ss][2], sq[ss][3]};
;         }
;         l[I0 + q] += rs2.x + rs2.y;
; #pragma unroll
;         for (int j = 0; j < 2; ++j) {
;             const v4u w = (v4u){cvtpk(sq[2 * j][0], sq[2 * j][1]), cvtpk(sq[2 * j][2], sq[2 * j][3]), cvtpk(sq[2 * j + 1][0], sq[2 * j + 1][1]), cvtpk(sq[2 * j + 1][2], sq[2 * j + 1][3])};
;             pb[q][j] = __builtin_bit_cast(bf16x8, w);
;         }
;     }
; #pragma unroll
;     for (int dt = 0; dt < 4; ++dt)
; #pragma unroll
;         for (int j = 0; j < 2; ++j) {
;             LAS unsigned char* vp = lds + VO + ((32 * j + 4 * fq + (fr >> 2)) * VSTR + 16 * dt + 4 * (fr & 3)) * 2;
;             const s16x4 lo = __builtin_bit_cast(s16x4, __builtin_amdgcn_ds_read_tr16_b64_v4i16((LAS v4i16_t*)vp));
;             const s16x4 hi = __builtin_bit_cast(s16x4, __builtin_amdgcn_ds_read_tr16_b64_v4i16((LAS v4i16_t*)(vp + 16 * VSTR * 2)));
;             const bf16x8 vf = (bf16x8){lo[0], lo[1], lo[2], lo[3], hi[0], hi[1], hi[2], hi[3]};
; #pragma unroll
;             for (int q = 0; q < NQ; ++q) o[I0 + q][dt] = __builtin_amdgcn_mfma_f32_16x16x32_bf16(vf, pb[q][j], o[I0 + q][dt], 0, 0, 0);
;         }
; }
; template <int DQK> __device__ __forceinline__ void x1_tile(LAS unsigned char* lds, const bf16x8 (&qf)[2][DQK / 32], const float (&m)[2], f32x4 (&s)[2][4], int fr, int fq) {
;     constexpr int NKS = DQK / 32;
; #pragma unroll
;     for (int q = 0; q < 2; ++q) { const float c = (m[q] > -1e29f) ? -m[q] : 0.f;
; #pragma unroll
;         for (int ss = 0; ss < 4; ++ss) s[q][ss] = (f32x4){c, c, c, c}; }
; #pragma unroll
;     for (int ss = 0; ss < 4; ++ss)
; #pragma unroll
;         for (int ks = 0; ks < NKS; ++ks) {
;             const bf16x8 kf = *(const LAS bf16x8*)(lds + k_off<DQK>(16 * ss + fr, 4 * ks + fq));
; #pragma unroll
.Lmla_nostage1:
	s_cmp_ge_u32 s49, s9
	s_cbranch_scc1 .Lmla_tail1
	ds_read_b64_tr_b16 v[220:221], v203 offset:16384
	ds_read_b64_tr_b16 v[222:223], v203 offset:18944
	ds_read_b64_tr_b16 v[224:225], v203 offset:21504
	ds_read_b64_tr_b16 v[226:227], v203 offset:24064
	ds_read_b64_tr_b16 v[228:229], v203 offset:16416
	ds_read_b64_tr_b16 v[230:231], v203 offset:18976
	ds_read_b64_tr_b16 v[232:233], v203 offset:21536
	ds_read_b64_tr_b16 v[234:235], v203 offset:24096
	ds_read_b128 v[236:239], v195 offset:26624
	ds_read_b128 v[240:243], v196 offset:26624
	ds_read_b128 v[244:247], v202 offset:26624
	s_waitcnt lgkmcnt(2)
	v_exp_f32_e32 v24, v24
	v_mfma_f32_16x16x32_bf16 v[100:103], v[236:239], v[0:3], v[204:207]
	v_exp_f32_e64 v25, v25
	v_mfma_f32_16x16x32_bf16 v[116:119], v[236:239], v[12:15], v[252:255]
	ds_read_b128 v[236:239], v195 offset:30720
	s_waitcnt lgkmcnt(2)
	v_exp_f32_e32 v26, v26
	v_mfma_f32_16x16x32_bf16 v[100:103], v[240:243], v[4:7], v[100:103]
	v_exp_f32_e64 v27, v27
	v_mfma_f32_16x16x32_bf16 v[116:119], v[240:243], v[16:19], v[116:119]
	ds_read_b128 v[240:243], v196 offset:30720
	s_waitcnt lgkmcnt(2)
	v_exp_f32_e32 v28, v28
	v_mfma_f32_16x16x32_bf16 v[100:103], v[244:247], v[8:11], v[100:103]
	v_exp_f32_e64 v29, v29
	v_mfma_f32_16x16x32_bf16 v[116:119], v[244:247], v[20:23], v[116:119]
	ds_read_b128 v[244:247], v202 offset:30720
	s_waitcnt lgkmcnt(2)
	v_exp_f32_e32 v30, v30
	v_mfma_f32_16x16x32_bf16 v[104:107], v[236:239], v[0:3], v[204:207]
	v_exp_f32_e64 v31, v31
	v_mfma_f32_16x16x32_bf16 v[120:123], v[236:239], v[12:15], v[252:255]
	ds_read_b128 v[236:239], v195 offset:34816
	s_waitcnt lgkmcnt(2)
	v_exp_f32_e32 v32, v32
	v_mfma_f32_16x16x32_bf16 v[104:107], v[240:243], v[4:7], v[104:107]
	v_exp_f32_e64 v33, v33
	v_mfma_f32_16x16x32_bf16 v[120:123], v[240:243], v[16:19], v[120:123]
	ds_read_b128 v[240:243], v196 offset:34816
	s_waitcnt lgkmcnt(2)
	v_exp_f32_e32 v34, v34
	v_mfma_f32_16x16x32_bf16 v[104:107], v[244:247], v[8:11], v[104:107]
	v_exp_f32_e64 v35, v35
	v_mfma_f32_16x16x32_bf16 v[120:123], v[244:247], v[20:23], v[120:123]
	ds_read_b128 v[244:247], v202 offset:34816
	s_waitcnt lgkmcnt(2)
	v_exp_f32_e32 v36, v36
	v_mfma_f32_16x16x32_bf16 v[108:111], v[236:239], v[0:3], v[204:207]
	v_exp_f32_e64 v37, v37
	v_mfma_f32_16x16x32_bf16 v[124:127], v[236:239], v[12:15], v[252:255]
	ds_read_b128 v[236:239], v195 offset:38912
	s_waitcnt lgkmcnt(2)
	v_exp_f32_e32 v38, v38
	v_mfma_f32_16x16x32_bf16 v[108:111], v[240:243], v[4:7], v[108:111]
	v_exp_f32_e64 v39, v39
	v_mfma_f32_16x16x32_bf16 v[124:127], v[240:243], v[16:19], v[124:127]
	ds_read_b128 v[240:243], v196 offset:38912
	s_waitcnt lgkmcnt(2)
	v_exp_f32_e32 v40, v40
	v_mfma_f32_16x16x32_bf16 v[108:111], v[244:247], v[8:11], v[108:111]
	v_exp_f32_e64 v41, v41
	v_mfma_f32_16x16x32_bf16 v[124:127], v[244:247], v[20:23], v[124:127]
	ds_read_b128 v[244:247], v202 offset:38912
	s_waitcnt lgkmcnt(2)
	v_exp_f32_e32 v42, v42
	v_mfma_f32_16x16x32_bf16 v[112:115], v[236:239], v[0:3], v[204:207]
	v_exp_f32_e64 v43, v43
	v_mfma_f32_16x16x32_bf16 v[128:131], v[236:239], v[12:15], v[252:255]
	ds_read_b64_tr_b16 v[236:237], v203 offset:16448
	ds_read_b64_tr_b16 v[238:239], v203 offset:19008
	s_waitcnt lgkmcnt(3)
	v_exp_f32_e32 v44, v44
	v_mfma_f32_16x16x32_bf16 v[112:115], v[240:243], v[4:7], v[112:115]
	v_exp_f32_e64 v45, v45
	v_mfma_f32_16x16x32_bf16 v[128:131], v[240:243], v[16:19], v[128:131]
	ds_read_b64_tr_b16 v[240:241], v203 offset:21568
	ds_read_b64_tr_b16 v[242:243], v203 offset:24128
	s_waitcnt lgkmcnt(4)
	v_exp_f32_e32 v46, v46
	v_mfma_f32_16x16x32_bf16 v[112:115], v[244:247], v[8:11], v[112:115]
	v_exp_f32_e64 v47, v47
	v_mfma_f32_16x16x32_bf16 v[128:131], v[244:247], v[20:23], v[128:131]
	ds_read_b64_tr_b16 v[244:245], v203 offset:16480
	ds_read_b64_tr_b16 v[246:247], v203 offset:19040
	v_exp_f32_e32 v212, v212
	v_exp_f32_e32 v213, v213
	v_exp_f32_e32 v214, v214
	v_exp_f32_e32 v215, v215
	v_exp_f32_e32 v216, v216
	v_exp_f32_e32 v217, v217
	v_exp_f32_e32 v218, v218
	v_exp_f32_e32 v219, v219
	v_cvt_pk_bf16_f32 v132, v24, v25
	v_cvt_pk_bf16_f32 v133, v26, v27
	v_cvt_pk_bf16_f32 v134, v28, v29
	v_cvt_pk_bf16_f32 v135, v30, v31
	v_cvt_pk_bf16_f32 v136, v32, v33
	v_cvt_pk_bf16_f32 v137, v34, v35
	v_cvt_pk_bf16_f32 v138, v36, v37
	v_cvt_pk_bf16_f32 v139, v38, v39
	v_cvt_pk_bf16_f32 v140, v40, v41
	v_cvt_pk_bf16_f32 v141, v42, v43
	v_cvt_pk_bf16_f32 v142, v44, v45
	v_cvt_pk_bf16_f32 v143, v46, v47
	v_cvt_pk_bf16_f32 v52, v212, v213
	v_cvt_pk_bf16_f32 v53, v214, v215
	v_cvt_pk_bf16_f32 v54, v216, v217
	v_cvt_pk_bf16_f32 v55, v218, v219
	s_waitcnt lgkmcnt(15)
	s_nop 0
	v_mfma_f32_16x16x32_bf16 v[96:99], v[220:223], v[132:135], v[96:99]
	v_add_f32_e32 v24, v24, v25
	v_add_f32_e32 v26, v26, v27
	v_mfma_f32_16x16x32_bf16 v[84:87], v[220:223], v[140:143], v[84:87]
	v_add_f32_e32 v28, v28, v29
	v_add_f32_e32 v30, v30, v31
	v_mfma_f32_16x16x32_bf16 v[96:99], v[224:227], v[136:139], v[96:99]
	v_add_f32_e32 v32, v32, v33
	v_add_f32_e32 v34, v34, v35
	v_mfma_f32_16x16x32_bf16 v[84:87], v[224:227], v[52:55], v[84:87]
	v_add_f32_e32 v36, v36, v37
	v_add_f32_e32 v38, v38, v39
	ds_read_b64_tr_b16 v[220:221], v203 offset:21600
	ds_read_b64_tr_b16 v[222:223], v203 offset:24160
	v_mfma_f32_16x16x32_bf16 v[88:91], v[228:231], v[132:135], v[88:91]
	v_add_f32_e32 v24, v24, v26
	v_add_f32_e32 v28, v28, v30
	v_mfma_f32_16x16x32_bf16 v[76:79], v[228:231], v[140:143], v[76:79]
	v_add_f32_e32 v32, v32, v34
	v_add_f32_e32 v36, v36, v38
	v_mfma_f32_16x16x32_bf16 v[88:91], v[232:235], v[136:139], v[88:91]
	v_add_f32_e32 v24, v24, v28
	v_add_f32_e32 v32, v32, v36
	v_mfma_f32_16x16x32_bf16 v[76:79], v[232:235], v[52:55], v[76:79]
	v_add_f32_e32 v24, v24, v32
	v_add_f32_e32 v165, v165, v24
	s_waitcnt lgkmcnt(0)
	s_nop 0
	v_mfma_f32_16x16x32_bf16 v[92:95], v[236:239], v[132:135], v[92:95]
	v_add_f32_e32 v40, v40, v41
	v_add_f32_e32 v42, v42, v43
	v_mfma_f32_16x16x32_bf16 v[80:83], v[236:239], v[140:143], v[80:83]
	v_add_f32_e32 v44, v44, v45
	v_add_f32_e32 v46, v46, v47
	v_mfma_f32_16x16x32_bf16 v[92:95], v[240:243], v[136:139], v[92:95]
	v_add_f32_e32 v212, v212, v213
	v_add_f32_e32 v214, v214, v215
	v_mfma_f32_16x16x32_bf16 v[80:83], v[240:243], v[52:55], v[80:83]
	v_add_f32_e32 v216, v216, v217
	v_add_f32_e32 v218, v218, v219
	v_mfma_f32_16x16x32_bf16 v[48:51], v[244:247], v[132:135], v[48:51]
	v_add_f32_e32 v40, v40, v42
	v_add_f32_e32 v44, v44, v46
	v_mfma_f32_16x16x32_bf16 v[56:59], v[244:247], v[140:143], v[56:59]
	v_add_f32_e32 v212, v212, v214
	v_add_f32_e32 v216, v216, v218
	v_mfma_f32_16x16x32_bf16 v[48:51], v[220:223], v[136:139], v[48:51]
	v_add_f32_e32 v40, v40, v44
	v_add_f32_e32 v212, v212, v216
	v_mfma_f32_16x16x32_bf16 v[56:59], v[220:223], v[52:55], v[56:59]
	v_add_f32_e32 v40, v40, v212
	v_add_f32_e32 v164, v164, v40
	s_add_i32 s32, s49, 1
	s_cmp_eq_u32 s32, s9
	s_cbranch_scc1 .Lmla_mask1

; #define LAS __attribute__((address_space(3)))
; template <int I0, int NQ, int VO> __device__ __forceinline__ void tile_y(LAS unsigned char* lds, float (&l)[2], f32x4 (&o)[2][4], f32x4 (&s)[2][4], int fr, int fq) {
;     bf16x8 pb[NQ][2];
; #pragma unroll
;     for (int q = 0; q < NQ; ++q) {
;         f32x4 (&sq)[4] = s[I0 + q];
;         f32x2_t rs2 = {0.f, 0.f};
; #pragma unroll
;         for (int ss = 0; ss < 4; ++ss) {
; #pragma unroll
;             for (int i = 0; i < 4; ++i) sq[ss][i] = __builtin_amdgcn_exp2f(sq[ss][i]);
;             rs2 += (f32x2_t){sq[ss][0], sq[ss][1]}; rs2 += (f32x2_t){sq[ss][2], sq[ss][3]};
;         }
;         l[I0 + q] += rs2.x + rs2.y;
; #pragma unroll
;         for (int j = 0; j < 2; ++j) {
;             const v4u w = (v4u){cvtpk(sq[2 * j][0], sq[2 * j][1]), cvtpk(sq[2 * j][2], sq[2 * j][3]), cvtpk(sq[2 * j + 1][0], sq[2 * j + 1][1]), cvtpk(sq[2 * j + 1][2], sq[2 * j + 1][3])};
;             pb[q][j] = __builtin_bit_cast(bf16x8, w);
;         }
;     }
; #pragma unroll
;     for (int dt = 0; dt < 4; ++dt)
; #pragma unroll
;         for (int j = 0; j < 2; ++j) {
;             LAS unsigned char* vp = lds + VO + ((32 * j + 4 * fq + (fr >> 2)) * VSTR + 16 * dt + 4 * (fr & 3)) * 2;
;             const s16x4 lo = __builtin_bit_cast(s16x4, __builtin_amdgcn_ds_read_tr16_b64_v4i16((LAS v4i16_t*)vp));
;             const s16x4 hi = __builtin_bit_cast(s16x4, __builtin_amdgcn_ds_read_tr16_b64_v4i16((LAS v4i16_t*)(vp + 16 * VSTR * 2)));
;             const bf16x8 vf = (bf16x8){lo[0], lo[1], lo[2], lo[3], hi[0], hi[1], hi[2], hi[3]};
; #pragma unroll
;             for (int q = 0; q < NQ; ++q) o[I0 + q][dt] = __builtin_amdgcn_mfma_f32_16x16x32_bf16(vf, pb[q][j], o[I0 + q][dt], 0, 0, 0);
;         }
; }
; template <int DQK> __device__ __forceinline__ void x1_tile(LAS unsigned char* lds, const bf16x8 (&qf)[2][DQK / 32], const float (&m)[2], f32x4 (&s)[2][4], int fr, int fq) {
;     constexpr int NKS = DQK / 32;
; #pragma unroll
;     for (int q = 0; q < 2; ++q) { const float c = (m[q] > -1e29f) ? -m[q] : 0.f;
; #pragma unroll
;         for (int ss = 0; ss < 4; ++ss) s[q][ss] = (f32x4){c, c, c, c}; }
; #pragma unroll
;     for (int ss = 0; ss < 4; ++ss)
; #pragma unroll
;         for (int ks = 0; ks < NKS; ++ks) {
;             const bf16x8 kf = *(const LAS bf16x8*)(lds + k_off<DQK>(16 * ss + fr, 4 * ks + fq));
; #pragma unroll
.Lmla_nostage2:
	s_cmp_ge_u32 s49, s9
	s_cbranch_scc1 .Lmla_tail2
	ds_read_b64_tr_b16 v[220:221], v203 offset:43008
	ds_read_b64_tr_b16 v[222:223], v203 offset:45568
	ds_read_b64_tr_b16 v[224:225], v203 offset:48128
	ds_read_b64_tr_b16 v[226:227], v203 offset:50688
	ds_read_b64_tr_b16 v[228:229], v203 offset:43040
	ds_read_b64_tr_b16 v[230:231], v203 offset:45600
	ds_read_b64_tr_b16 v[232:233], v203 offset:48160
	ds_read_b64_tr_b16 v[234:235], v203 offset:50720
	ds_read_b128 v[236:239], v199
	ds_read_b128 v[240:243], v201
	ds_read_b128 v[244:247], v210
	s_waitcnt lgkmcnt(2)
	v_exp_f32_e32 v100, v100
	v_mfma_f32_16x16x32_bf16 v[24:27], v[236:239], v[0:3], v[204:207]
	v_exp_f32_e64 v101, v101
	v_mfma_f32_16x16x32_bf16 v[40:43], v[236:239], v[12:15], v[252:255]
	ds_read_b128 v[236:239], v199 offset:4096
	s_waitcnt lgkmcnt(2)
	v_exp_f32_e32 v102, v102
	v_mfma_f32_16x16x32_bf16 v[24:27], v[240:243], v[4:7], v[24:27]
	v_exp_f32_e64 v103, v103
	v_mfma_f32_16x16x32_bf16 v[40:43], v[240:243], v[16:19], v[40:43]
	ds_read_b128 v[240:243], v201 offset:4096
	s_waitcnt lgkmcnt(2)
	v_exp_f32_e32 v104, v104
	v_mfma_f32_16x16x32_bf16 v[24:27], v[244:247], v[8:11], v[24:27]
	v_exp_f32_e64 v105, v105
	v_mfma_f32_16x16x32_bf16 v[40:43], v[244:247], v[20:23], v[40:43]
	ds_read_b128 v[244:247], v210 offset:4096
	s_waitcnt lgkmcnt(2)
	v_exp_f32_e32 v106, v106
	v_mfma_f32_16x16x32_bf16 v[28:31], v[236:239], v[0:3], v[204:207]
	v_exp_f32_e64 v107, v107
	v_mfma_f32_16x16x32_bf16 v[44:47], v[236:239], v[12:15], v[252:255]
	ds_read_b128 v[236:239], v199 offset:8192
	s_waitcnt lgkmcnt(2)
	v_exp_f32_e32 v108, v108
	v_mfma_f32_16x16x32_bf16 v[28:31], v[240:243], v[4:7], v[28:31]
	v_exp_f32_e64 v109, v109
	v_mfma_f32_16x16x32_bf16 v[44:47], v[240:243], v[16:19], v[44:47]
	ds_read_b128 v[240:243], v201 offset:8192
	s_waitcnt lgkmcnt(2)
	v_exp_f32_e32 v110, v110
	v_mfma_f32_16x16x32_bf16 v[28:31], v[244:247], v[8:11], v[28:31]
	v_exp_f32_e64 v111, v111
	v_mfma_f32_16x16x32_bf16 v[44:47], v[244:247], v[20:23], v[44:47]
	ds_read_b128 v[244:247], v210 offset:8192
	s_waitcnt lgkmcnt(2)
	v_exp_f32_e32 v112, v112
	v_mfma_f32_16x16x32_bf16 v[32:35], v[236:239], v[0:3], v[204:207]
	v_exp_f32_e64 v113, v113
	v_mfma_f32_16x16x32_bf16 v[212:215], v[236:239], v[12:15], v[252:255]
	ds_read_b128 v[236:239], v199 offset:12288
	s_waitcnt lgkmcnt(2)
	v_exp_f32_e32 v114, v114
	v_mfma_f32_16x16x32_bf16 v[32:35], v[240:243], v[4:7], v[32:35]
	v_exp_f32_e64 v115, v115
	v_mfma_f32_16x16x32_bf16 v[212:215], v[240:243], v[16:19], v[212:215]
	ds_read_b128 v[240:243], v201 offset:12288
	s_waitcnt lgkmcnt(2)
	v_exp_f32_e32 v116, v116
	v_mfma_f32_16x16x32_bf16 v[32:35], v[244:247], v[8:11], v[32:35]
	v_exp_f32_e64 v117, v117
	v_mfma_f32_16x16x32_bf16 v[212:215], v[244:247], v[20:23], v[212:215]
	ds_read_b128 v[244:247], v210 offset:12288
	s_waitcnt lgkmcnt(2)
	v_exp_f32_e32 v118, v118
	v_mfma_f32_16x16x32_bf16 v[36:39], v[236:239], v[0:3], v[204:207]
	v_exp_f32_e64 v119, v119
	v_mfma_f32_16x16x32_bf16 v[216:219], v[236:239], v[12:15], v[252:255]
	ds_read_b64_tr_b16 v[236:237], v203 offset:43072
	ds_read_b64_tr_b16 v[238:239], v203 offset:45632
	s_waitcnt lgkmcnt(3)
	v_exp_f32_e32 v120, v120
	v_mfma_f32_16x16x32_bf16 v[36:39], v[240:243], v[4:7], v[36:39]
	v_exp_f32_e64 v121, v121
	v_mfma_f32_16x16x32_bf16 v[216:219], v[240:243], v[16:19], v[216:219]
	ds_read_b64_tr_b16 v[240:241], v203 offset:48192
	ds_read_b64_tr_b16 v[242:243], v203 offset:50752
	s_waitcnt lgkmcnt(4)
	v_exp_f32_e32 v122, v122
	v_mfma_f32_16x16x32_bf16 v[36:39], v[244:247], v[8:11], v[36:39]
	v_exp_f32_e64 v123, v123
	v_mfma_f32_16x16x32_bf16 v[216:219], v[244:247], v[20:23], v[216:219]
	ds_read_b64_tr_b16 v[244:245], v203 offset:43104
	ds_read_b64_tr_b16 v[246:247], v203 offset:45664
	v_exp_f32_e32 v124, v124
	v_exp_f32_e32 v125, v125
	v_exp_f32_e32 v126, v126
	v_exp_f32_e32 v127, v127
	v_exp_f32_e32 v128, v128
	v_exp_f32_e32 v129, v129
	v_exp_f32_e32 v130, v130
	v_exp_f32_e32 v131, v131
	v_cvt_pk_bf16_f32 v132, v100, v101
	v_cvt_pk_bf16_f32 v133, v102, v103
	v_cvt_pk_bf16_f32 v134, v104, v105
	v_cvt_pk_bf16_f32 v135, v106, v107
	v_cvt_pk_bf16_f32 v136, v108, v109
	v_cvt_pk_bf16_f32 v137, v110, v111
	v_cvt_pk_bf16_f32 v138, v112, v113
	v_cvt_pk_bf16_f32 v139, v114, v115
	v_cvt_pk_bf16_f32 v140, v116, v117
	v_cvt_pk_bf16_f32 v141, v118, v119
	v_cvt_pk_bf16_f32 v142, v120, v121
	v_cvt_pk_bf16_f32 v143, v122, v123
	v_cvt_pk_bf16_f32 v52, v124, v125
	v_cvt_pk_bf16_f32 v53, v126, v127
	v_cvt_pk_bf16_f32 v54, v128, v129
	v_cvt_pk_bf16_f32 v55, v130, v131
	s_waitcnt lgkmcnt(15)
	s_nop 0
	v_mfma_f32_16x16x32_bf16 v[96:99], v[220:223], v[132:135], v[96:99]
	v_add_f32_e32 v100, v100, v101
	v_add_f32_e32 v102, v102, v103
	v_mfma_f32_16x16x32_bf16 v[84:87], v[220:223], v[140:143], v[84:87]
	v_add_f32_e32 v104, v104, v105
	v_add_f32_e32 v106, v106, v107
	v_mfma_f32_16x16x32_bf16 v[96:99], v[224:227], v[136:139], v[96:99]
	v_add_f32_e32 v108, v108, v109
	v_add_f32_e32 v110, v110, v111
	v_mfma_f32_16x16x32_bf16 v[84:87], v[224:227], v[52:55], v[84:87]
	v_add_f32_e32 v112, v112, v113
	v_add_f32_e32 v114, v114, v115
	ds_read_b64_tr_b16 v[220:221], v203 offset:48224
	ds_read_b64_tr_b16 v[222:223], v203 offset:50784
	v_mfma_f32_16x16x32_bf16 v[88:91], v[228:231], v[132:135], v[88:91]
	v_add_f32_e32 v100, v100, v102
	v_add_f32_e32 v104, v104, v106
	v_mfma_f32_16x16x32_bf16 v[76:79], v[228:231], v[140:143], v[76:79]
	v_add_f32_e32 v108, v108, v110
	v_add_f32_e32 v112, v112, v114
	v_mfma_f32_16x16x32_bf16 v[88:91], v[232:235], v[136:139], v[88:91]
	v_add_f32_e32 v100, v100, v104
	v_add_f32_e32 v108, v108, v112
	v_mfma_f32_16x16x32_bf16 v[76:79], v[232:235], v[52:55], v[76:79]
	v_add_f32_e32 v100, v100, v108
	v_add_f32_e32 v165, v165, v100
	s_waitcnt lgkmcnt(0)
	s_nop 0
	v_mfma_f32_16x16x32_bf16 v[92:95], v[236:239], v[132:135], v[92:95]
	v_add_f32_e32 v116, v116, v117
	v_add_f32_e32 v118, v118, v119
	v_mfma_f32_16x16x32_bf16 v[80:83], v[236:239], v[140:143], v[80:83]
	v_add_f32_e32 v120, v120, v121
	v_add_f32_e32 v122, v122, v123
	v_mfma_f32_16x16x32_bf16 v[92:95], v[240:243], v[136:139], v[92:95]
	v_add_f32_e32 v124, v124, v125
	v_add_f32_e32 v126, v126, v127
	v_mfma_f32_16x16x32_bf16 v[80:83], v[240:243], v[52:55], v[80:83]
	v_add_f32_e32 v128, v128, v129
	v_add_f32_e32 v130, v130, v131
	v_mfma_f32_16x16x32_bf16 v[48:51], v[244:247], v[132:135], v[48:51]
	v_add_f32_e32 v116, v116, v118
	v_add_f32_e32 v120, v120, v122
	v_mfma_f32_16x16x32_bf16 v[56:59], v[244:247], v[140:143], v[56:59]
	v_add_f32_e32 v124, v124, v126
	v_add_f32_e32 v128, v128, v130
	v_mfma_f32_16x16x32_bf16 v[48:51], v[220:223], v[136:139], v[48:51]
	v_add_f32_e32 v116, v116, v120
	v_add_f32_e32 v124, v124, v128
	v_mfma_f32_16x16x32_bf16 v[56:59], v[220:223], v[52:55], v[56:59]
	v_add_f32_e32 v116, v116, v124
	v_add_f32_e32 v164, v164, v116
	s_add_i32 s32, s49, 1
	s_cmp_eq_u32 s32, s9
	s_cbranch_scc1 .Lmla_mask2

; #define LAS __attribute__((address_space(3)))
; template <int I0, int NQ, int VO> __device__ __forceinline__ void tile_y(LAS unsigned char* lds, float (&l)[2], f32x4 (&o)[2][4], f32x4 (&s)[2][4], int fr, int fq) {
;     bf16x8 pb[NQ][2];
; #pragma unroll
;     for (int q = 0; q < NQ; ++q) {
;         f32x4 (&sq)[4] = s[I0 + q];
;         f32x2_t rs2 = {0.f, 0.f};
; #pragma unroll
;         for (int ss = 0; ss < 4; ++ss) {
; #pragma unroll
;             for (int i = 0; i < 4; ++i) sq[ss][i] = __builtin_amdgcn_exp2f(sq[ss][i]);
;             rs2 += (f32x2_t){sq[ss][0], sq[ss][1]}; rs2 += (f32x2_t){sq[ss][2], sq[ss][3]};
;         }
;         l[I0 + q] += rs2.x + rs2.y;
; #pragma unroll
;         for (int j = 0; j < 2; ++j) {
;             const v4u w = (v4u){cvtpk(sq[2 * j][0], sq[2 * j][1]), cvtpk(sq[2 * j][2], sq[2 * j][3]), cvtpk(sq[2 * j + 1][0], sq[2 * j + 1][1]), cvtpk(sq[2 * j + 1][2], sq[2 * j + 1][3])};
;             pb[q][j] = __builtin_bit_cast(bf16x8, w);
;         }
;     }
; #pragma unroll
;     for (int dt = 0; dt < 4; ++dt)
; #pragma unroll
;         for (int j = 0; j < 2; ++j) {
;             LAS unsigned char* vp = lds + VO + ((32 * j + 4 * fq + (fr >> 2)) * VSTR + 16 * dt + 4 * (fr & 3)) * 2;
;             const s16x4 lo = __builtin_bit_cast(s16x4, __builtin_amdgcn_ds_read_tr16_b64_v4i16((LAS v4i16_t*)vp));
;             const s16x4 hi = __builtin_bit_cast(s16x4, __builtin_amdgcn_ds_read_tr16_b64_v4i16((LAS v4i16_t*)(vp + 16 * VSTR * 2)));
;             const bf16x8 vf = (bf16x8){lo[0], lo[1], lo[2], lo[3], hi[0], hi[1], hi[2], hi[3]};
; #pragma unroll
;             for (int q = 0; q < NQ; ++q) o[I0 + q][dt] = __builtin_amdgcn_mfma_f32_16x16x32_bf16(vf, pb[q][j], o[I0 + q][dt], 0, 0, 0);
;         }
; }
; template <int DQK> __device__ __forceinline__ void x1_tile(LAS unsigned char* lds, const bf16x8 (&qf)[2][DQK / 32], const float (&m)[2], f32x4 (&s)[2][4], int fr, int fq) {
;     constexpr int NKS = DQK / 32;
; #pragma unroll
;     for (int q = 0; q < 2; ++q) { const float c = (m[q] > -1e29f) ? -m[q] : 0.f;
; #pragma unroll
;         for (int ss = 0; ss < 4; ++ss) s[q][ss] = (f32x4){c, c, c, c}; }
; #pragma unroll
;     for (int ss = 0; ss < 4; ++ss)
; #pragma unroll
;         for (int ks = 0; ks < NKS; ++ks) {
;             const bf16x8 kf = *(const LAS bf16x8*)(lds + k_off<DQK>(16 * ss + fr, 4 * ks + fq));
; #pragma unroll
.Lmla_nostage3:
	s_cmp_ge_u32 s49, s9
	s_cbranch_scc1 .Lmla_tail3
	ds_read_b64_tr_b16 v[220:221], v251 offset:16384
	ds_read_b64_tr_b16 v[222:223], v251 offset:18944
	ds_read_b64_tr_b16 v[224:225], v251 offset:21504
	ds_read_b64_tr_b16 v[226:227], v251 offset:24064
	ds_read_b64_tr_b16 v[228:229], v251 offset:16416
	ds_read_b64_tr_b16 v[230:231], v251 offset:18976
	ds_read_b64_tr_b16 v[232:233], v251 offset:21536
	ds_read_b64_tr_b16 v[234:235], v251 offset:24096
	ds_read_b128 v[236:239], v195
	ds_read_b128 v[240:243], v196
	ds_read_b128 v[244:247], v202
	s_waitcnt lgkmcnt(2)
	v_exp_f32_e32 v24, v24
	v_mfma_f32_16x16x32_bf16 v[100:103], v[236:239], v[0:3], v[204:207]
	v_exp_f32_e64 v25, v25
	v_mfma_f32_16x16x32_bf16 v[116:119], v[236:239], v[12:15], v[252:255]
	ds_read_b128 v[236:239], v195 offset:4096
	s_waitcnt lgkmcnt(2)
	v_exp_f32_e32 v26, v26
	v_mfma_f32_16x16x32_bf16 v[100:103], v[240:243], v[4:7], v[100:103]
	v_exp_f32_e64 v27, v27
	v_mfma_f32_16x16x32_bf16 v[116:119], v[240:243], v[16:19], v[116:119]
	ds_read_b128 v[240:243], v196 offset:4096
	s_waitcnt lgkmcnt(2)
	v_exp_f32_e32 v28, v28
	v_mfma_f32_16x16x32_bf16 v[100:103], v[244:247], v[8:11], v[100:103]
	v_exp_f32_e64 v29, v29
	v_mfma_f32_16x16x32_bf16 v[116:119], v[244:247], v[20:23], v[116:119]
	ds_read_b128 v[244:247], v202 offset:4096
	s_waitcnt lgkmcnt(2)
	v_exp_f32_e32 v30, v30
	v_mfma_f32_16x16x32_bf16 v[104:107], v[236:239], v[0:3], v[204:207]
	v_exp_f32_e64 v31, v31
	v_mfma_f32_16x16x32_bf16 v[120:123], v[236:239], v[12:15], v[252:255]
	ds_read_b128 v[236:239], v195 offset:8192
	s_waitcnt lgkmcnt(2)
	v_exp_f32_e32 v32, v32
	v_mfma_f32_16x16x32_bf16 v[104:107], v[240:243], v[4:7], v[104:107]
	v_exp_f32_e64 v33, v33
	v_mfma_f32_16x16x32_bf16 v[120:123], v[240:243], v[16:19], v[120:123]
	ds_read_b128 v[240:243], v196 offset:8192
	s_waitcnt lgkmcnt(2)
	v_exp_f32_e32 v34, v34
	v_mfma_f32_16x16x32_bf16 v[104:107], v[244:247], v[8:11], v[104:107]
	v_exp_f32_e64 v35, v35
	v_mfma_f32_16x16x32_bf16 v[120:123], v[244:247], v[20:23], v[120:123]
	ds_read_b128 v[244:247], v202 offset:8192
	s_waitcnt lgkmcnt(2)
	v_exp_f32_e32 v36, v36
	v_mfma_f32_16x16x32_bf16 v[108:111], v[236:239], v[0:3], v[204:207]
	v_exp_f32_e64 v37, v37
	v_mfma_f32_16x16x32_bf16 v[124:127], v[236:239], v[12:15], v[252:255]
	ds_read_b128 v[236:239], v195 offset:12288
	s_waitcnt lgkmcnt(2)
	v_exp_f32_e32 v38, v38
	v_mfma_f32_16x16x32_bf16 v[108:111], v[240:243], v[4:7], v[108:111]
	v_exp_f32_e64 v39, v39
	v_mfma_f32_16x16x32_bf16 v[124:127], v[240:243], v[16:19], v[124:127]
	ds_read_b128 v[240:243], v196 offset:12288
	s_waitcnt lgkmcnt(2)
	v_exp_f32_e32 v40, v40
	v_mfma_f32_16x16x32_bf16 v[108:111], v[244:247], v[8:11], v[108:111]
	v_exp_f32_e64 v41, v41
	v_mfma_f32_16x16x32_bf16 v[124:127], v[244:247], v[20:23], v[124:127]
	ds_read_b128 v[244:247], v202 offset:12288
	s_waitcnt lgkmcnt(2)
	v_exp_f32_e32 v42, v42
	v_mfma_f32_16x16x32_bf16 v[112:115], v[236:239], v[0:3], v[204:207]
	v_exp_f32_e64 v43, v43
	v_mfma_f32_16x16x32_bf16 v[128:131], v[236:239], v[12:15], v[252:255]
	ds_read_b64_tr_b16 v[236:237], v251 offset:16448
	ds_read_b64_tr_b16 v[238:239], v251 offset:19008
	s_waitcnt lgkmcnt(3)
	v_exp_f32_e32 v44, v44
	v_mfma_f32_16x16x32_bf16 v[112:115], v[240:243], v[4:7], v[112:115]
	v_exp_f32_e64 v45, v45
	v_mfma_f32_16x16x32_bf16 v[128:131], v[240:243], v[16:19], v[128:131]
	ds_read_b64_tr_b16 v[240:241], v251 offset:21568
	ds_read_b64_tr_b16 v[242:243], v251 offset:24128
	s_waitcnt lgkmcnt(4)
	v_exp_f32_e32 v46, v46
	v_mfma_f32_16x16x32_bf16 v[112:115], v[244:247], v[8:11], v[112:115]
	v_exp_f32_e64 v47, v47
	v_mfma_f32_16x16x32_bf16 v[128:131], v[244:247], v[20:23], v[128:131]
	ds_read_b64_tr_b16 v[244:245], v251 offset:16480
	ds_read_b64_tr_b16 v[246:247], v251 offset:19040
	v_exp_f32_e32 v212, v212
	v_exp_f32_e32 v213, v213
	v_exp_f32_e32 v214, v214
	v_exp_f32_e32 v215, v215
	v_exp_f32_e32 v216, v216
	v_exp_f32_e32 v217, v217
	v_exp_f32_e32 v218, v218
	v_exp_f32_e32 v219, v219
	v_cvt_pk_bf16_f32 v132, v24, v25
	v_cvt_pk_bf16_f32 v133, v26, v27
	v_cvt_pk_bf16_f32 v134, v28, v29
	v_cvt_pk_bf16_f32 v135, v30, v31
	v_cvt_pk_bf16_f32 v136, v32, v33
	v_cvt_pk_bf16_f32 v137, v34, v35
	v_cvt_pk_bf16_f32 v138, v36, v37
	v_cvt_pk_bf16_f32 v139, v38, v39
	v_cvt_pk_bf16_f32 v140, v40, v41
	v_cvt_pk_bf16_f32 v141, v42, v43
	v_cvt_pk_bf16_f32 v142, v44, v45
	v_cvt_pk_bf16_f32 v143, v46, v47
	v_cvt_pk_bf16_f32 v52, v212, v213
	v_cvt_pk_bf16_f32 v53, v214, v215
	v_cvt_pk_bf16_f32 v54, v216, v217
	v_cvt_pk_bf16_f32 v55, v218, v219
	s_waitcnt lgkmcnt(15)
	s_nop 0
	v_mfma_f32_16x16x32_bf16 v[96:99], v[220:223], v[132:135], v[96:99]
	v_add_f32_e32 v24, v24, v25
	v_add_f32_e32 v26, v26, v27
	v_mfma_f32_16x16x32_bf16 v[84:87], v[220:223], v[140:143], v[84:87]
	v_add_f32_e32 v28, v28, v29
	v_add_f32_e32 v30, v30, v31
	v_mfma_f32_16x16x32_bf16 v[96:99], v[224:227], v[136:139], v[96:99]
	v_add_f32_e32 v32, v32, v33
	v_add_f32_e32 v34, v34, v35
	v_mfma_f32_16x16x32_bf16 v[84:87], v[224:227], v[52:55], v[84:87]
	v_add_f32_e32 v36, v36, v37
	v_add_f32_e32 v38, v38, v39
	ds_read_b64_tr_b16 v[220:221], v251 offset:21600
	ds_read_b64_tr_b16 v[222:223], v251 offset:24160
	v_mfma_f32_16x16x32_bf16 v[88:91], v[228:231], v[132:135], v[88:91]
	v_add_f32_e32 v24, v24, v26
	v_add_f32_e32 v28, v28, v30
	v_mfma_f32_16x16x32_bf16 v[76:79], v[228:231], v[140:143], v[76:79]
	v_add_f32_e32 v32, v32, v34
	v_add_f32_e32 v36, v36, v38
	v_mfma_f32_16x16x32_bf16 v[88:91], v[232:235], v[136:139], v[88:91]
	v_add_f32_e32 v24, v24, v28
	v_add_f32_e32 v32, v32, v36
	v_mfma_f32_16x16x32_bf16 v[76:79], v[232:235], v[52:55], v[76:79]
	v_add_f32_e32 v24, v24, v32
	v_add_f32_e32 v165, v165, v24
	s_waitcnt lgkmcnt(0)
	s_nop 0
	v_mfma_f32_16x16x32_bf16 v[92:95], v[236:239], v[132:135], v[92:95]
	v_add_f32_e32 v40, v40, v41
	v_add_f32_e32 v42, v42, v43
	v_mfma_f32_16x16x32_bf16 v[80:83], v[236:239], v[140:143], v[80:83]
	v_add_f32_e32 v44, v44, v45
	v_add_f32_e32 v46, v46, v47
	v_mfma_f32_16x16x32_bf16 v[92:95], v[240:243], v[136:139], v[92:95]
	v_add_f32_e32 v212, v212, v213
	v_add_f32_e32 v214, v214, v215
	v_mfma_f32_16x16x32_bf16 v[80:83], v[240:243], v[52:55], v[80:83]
	v_add_f32_e32 v216, v216, v217
	v_add_f32_e32 v218, v218, v219
	v_mfma_f32_16x16x32_bf16 v[48:51], v[244:247], v[132:135], v[48:51]
	v_add_f32_e32 v40, v40, v42
	v_add_f32_e32 v44, v44, v46
	v_mfma_f32_16x16x32_bf16 v[56:59], v[244:247], v[140:143], v[56:59]
	v_add_f32_e32 v212, v212, v214
	v_add_f32_e32 v216, v216, v218
	v_mfma_f32_16x16x32_bf16 v[48:51], v[220:223], v[136:139], v[48:51]
	v_add_f32_e32 v40, v40, v44
	v_add_f32_e32 v212, v212, v216
	v_mfma_f32_16x16x32_bf16 v[56:59], v[220:223], v[52:55], v[56:59]
	v_add_f32_e32 v40, v40, v212
	v_add_f32_e32 v164, v164, v40
	s_add_i32 s32, s49, 1
	s_cmp_eq_u32 s32, s9
	s_cbranch_scc1 .Lmla_mask3

; #define LAS __attribute__((address_space(3)))
; template <int I0, int NQ, int VO> __device__ __forceinline__ void tile_y(LAS unsigned char* lds, float (&l)[2], f32x4 (&o)[2][4], f32x4 (&s)[2][4], int fr, int fq) {
;     bf16x8 pb[NQ][2];
; #pragma unroll
;     for (int q = 0; q < NQ; ++q) {
;         f32x4 (&sq)[4] = s[I0 + q];
;         f32x2_t rs2 = {0.f, 0.f};
; #pragma unroll
;         for (int ss = 0; ss < 4; ++ss) {
; #pragma unroll
;             for (int i = 0; i < 4; ++i) sq[ss][i] = __builtin_amdgcn_exp2f(sq[ss][i]);
;             rs2 += (f32x2_t){sq[ss][0], sq[ss][1]}; rs2 += (f32x2_t){sq[ss][2], sq[ss][3]};
;         }
;         l[I0 + q] += rs2.x + rs2.y;
; #pragma unroll
;         for (int j = 0; j < 2; ++j) {
;             const v4u w = (v4u){cvtpk(sq[2 * j][0], sq[2 * j][1]), cvtpk(sq[2 * j][2], sq[2 * j][3]), cvtpk(sq[2 * j + 1][0], sq[2 * j + 1][1]), cvtpk(sq[2 * j + 1][2], sq[2 * j + 1][3])};
;             pb[q][j] = __builtin_bit_cast(bf16x8, w);
;         }
;     }
; #pragma unroll
;     for (int dt = 0; dt < 4; ++dt)
; #pragma unroll
;         for (int j = 0; j < 2; ++j) {
;             LAS unsigned char* vp = lds + VO + ((32 * j + 4 * fq + (fr >> 2)) * VSTR + 16 * dt + 4 * (fr & 3)) * 2;
;             const s16x4 lo = __builtin_bit_cast(s16x4, __builtin_amdgcn_ds_read_tr16_b64_v4i16((LAS v4i16_t*)vp));
;             const s16x4 hi = __builtin_bit_cast(s16x4, __builtin_amdgcn_ds_read_tr16_b64_v4i16((LAS v4i16_t*)(vp + 16 * VSTR * 2)));
;             const bf16x8 vf = (bf16x8){lo[0], lo[1], lo[2], lo[3], hi[0], hi[1], hi[2], hi[3]};
; #pragma unroll
;             for (int q = 0; q < NQ; ++q) o[I0 + q][dt] = __builtin_amdgcn_mfma_f32_16x16x32_bf16(vf, pb[q][j], o[I0 + q][dt], 0, 0, 0);
;         }
; }
; template <int DQK> __device__ __forceinline__ void x1_tile(LAS unsigned char* lds, const bf16x8 (&qf)[2][DQK / 32], const float (&m)[2], f32x4 (&s)[2][4], int fr, int fq) {
;     constexpr int NKS = DQK / 32;
; #pragma unroll
;     for (int q = 0; q < 2; ++q) { const float c = (m[q] > -1e29f) ? -m[q] : 0.f;
; #pragma unroll
;         for (int ss = 0; ss < 4; ++ss) s[q][ss] = (f32x4){c, c, c, c}; }
; #pragma unroll
;     for (int ss = 0; ss < 4; ++ss)
; #pragma unroll
;         for (int ks = 0; ks < NKS; ++ks) {
;             const bf16x8 kf = *(const LAS bf16x8*)(lds + k_off<DQK>(16 * ss + fr, 4 * ks + fq));
; #pragma unroll
.Lmla_nostage4:
	s_cmp_ge_u32 s49, s9
	s_cbranch_scc1 .Lmla_tail4
	ds_read_b64_tr_b16 v[220:221], v203 offset:16384
	ds_read_b64_tr_b16 v[222:223], v203 offset:18944
	ds_read_b64_tr_b16 v[224:225], v203 offset:21504
	ds_read_b64_tr_b16 v[226:227], v203 offset:24064
	ds_read_b64_tr_b16 v[228:229], v203 offset:16416
	ds_read_b64_tr_b16 v[230:231], v203 offset:18976
	ds_read_b64_tr_b16 v[232:233], v203 offset:21536
	ds_read_b64_tr_b16 v[234:235], v203 offset:24096
	ds_read_b128 v[236:239], v195 offset:26624
	ds_read_b128 v[240:243], v196 offset:26624
	ds_read_b128 v[244:247], v202 offset:26624
	s_waitcnt lgkmcnt(2)
	v_exp_f32_e32 v100, v100
	v_mfma_f32_16x16x32_bf16 v[24:27], v[236:239], v[0:3], v[204:207]
	v_exp_f32_e64 v101, v101
	v_mfma_f32_16x16x32_bf16 v[40:43], v[236:239], v[12:15], v[252:255]
	ds_read_b128 v[236:239], v195 offset:30720
	s_waitcnt lgkmcnt(2)
	v_exp_f32_e32 v102, v102
	v_mfma_f32_16x16x32_bf16 v[24:27], v[240:243], v[4:7], v[24:27]
	v_exp_f32_e64 v103, v103
	v_mfma_f32_16x16x32_bf16 v[40:43], v[240:243], v[16:19], v[40:43]
	ds_read_b128 v[240:243], v196 offset:30720
	s_waitcnt lgkmcnt(2)
	v_exp_f32_e32 v104, v104
	v_mfma_f32_16x16x32_bf16 v[24:27], v[244:247], v[8:11], v[24:27]
	v_exp_f32_e64 v105, v105
	v_mfma_f32_16x16x32_bf16 v[40:43], v[244:247], v[20:23], v[40:43]
	ds_read_b128 v[244:247], v202 offset:30720
	s_waitcnt lgkmcnt(2)
	v_exp_f32_e32 v106, v106
	v_mfma_f32_16x16x32_bf16 v[28:31], v[236:239], v[0:3], v[204:207]
	v_exp_f32_e64 v107, v107
	v_mfma_f32_16x16x32_bf16 v[44:47], v[236:239], v[12:15], v[252:255]
	ds_read_b128 v[236:239], v195 offset:34816
	s_waitcnt lgkmcnt(2)
	v_exp_f32_e32 v108, v108
	v_mfma_f32_16x16x32_bf16 v[28:31], v[240:243], v[4:7], v[28:31]
	v_exp_f32_e64 v109, v109
	v_mfma_f32_16x16x32_bf16 v[44:47], v[240:243], v[16:19], v[44:47]
	ds_read_b128 v[240:243], v196 offset:34816
	s_waitcnt lgkmcnt(2)
	v_exp_f32_e32 v110, v110
	v_mfma_f32_16x16x32_bf16 v[28:31], v[244:247], v[8:11], v[28:31]
	v_exp_f32_e64 v111, v111
	v_mfma_f32_16x16x32_bf16 v[44:47], v[244:247], v[20:23], v[44:47]
	ds_read_b128 v[244:247], v202 offset:34816
	s_waitcnt lgkmcnt(2)
	v_exp_f32_e32 v112, v112
	v_mfma_f32_16x16x32_bf16 v[32:35], v[236:239], v[0:3], v[204:207]
	v_exp_f32_e64 v113, v113
	v_mfma_f32_16x16x32_bf16 v[212:215], v[236:239], v[12:15], v[252:255]
	ds_read_b128 v[236:239], v195 offset:38912
	s_waitcnt lgkmcnt(2)
	v_exp_f32_e32 v114, v114
	v_mfma_f32_16x16x32_bf16 v[32:35], v[240:243], v[4:7], v[32:35]
	v_exp_f32_e64 v115, v115
	v_mfma_f32_16x16x32_bf16 v[212:215], v[240:243], v[16:19], v[212:215]
	ds_read_b128 v[240:243], v196 offset:38912
	s_waitcnt lgkmcnt(2)
	v_exp_f32_e32 v116, v116
	v_mfma_f32_16x16x32_bf16 v[32:35], v[244:247], v[8:11], v[32:35]
	v_exp_f32_e64 v117, v117
	v_mfma_f32_16x16x32_bf16 v[212:215], v[244:247], v[20:23], v[212:215]
	ds_read_b128 v[244:247], v202 offset:38912
	s_waitcnt lgkmcnt(2)
	v_exp_f32_e32 v118, v118
	v_mfma_f32_16x16x32_bf16 v[36:39], v[236:239], v[0:3], v[204:207]
	v_exp_f32_e64 v119, v119
	v_mfma_f32_16x16x32_bf16 v[216:219], v[236:239], v[12:15], v[252:255]
	ds_read_b64_tr_b16 v[236:237], v203 offset:16448
	ds_read_b64_tr_b16 v[238:239], v203 offset:19008
	s_waitcnt lgkmcnt(3)
	v_exp_f32_e32 v120, v120
	v_mfma_f32_16x16x32_bf16 v[36:39], v[240:243], v[4:7], v[36:39]
	v_exp_f32_e64 v121, v121
	v_mfma_f32_16x16x32_bf16 v[216:219], v[240:243], v[16:19], v[216:219]
	ds_read_b64_tr_b16 v[240:241], v203 offset:21568
	ds_read_b64_tr_b16 v[242:243], v203 offset:24128
	s_waitcnt lgkmcnt(4)
	v_exp_f32_e32 v122, v122
	v_mfma_f32_16x16x32_bf16 v[36:39], v[244:247], v[8:11], v[36:39]
	v_exp_f32_e64 v123, v123
	v_mfma_f32_16x16x32_bf16 v[216:219], v[244:247], v[20:23], v[216:219]
	ds_read_b64_tr_b16 v[244:245], v203 offset:16480
	ds_read_b64_tr_b16 v[246:247], v203 offset:19040
	v_exp_f32_e32 v124, v124
	v_exp_f32_e32 v125, v125
	v_exp_f32_e32 v126, v126
	v_exp_f32_e32 v127, v127
	v_exp_f32_e32 v128, v128
	v_exp_f32_e32 v129, v129
	v_exp_f32_e32 v130, v130
	v_exp_f32_e32 v131, v131
	v_cvt_pk_bf16_f32 v132, v100, v101
	v_cvt_pk_bf16_f32 v133, v102, v103
	v_cvt_pk_bf16_f32 v134, v104, v105
	v_cvt_pk_bf16_f32 v135, v106, v107
	v_cvt_pk_bf16_f32 v136, v108, v109
	v_cvt_pk_bf16_f32 v137, v110, v111
	v_cvt_pk_bf16_f32 v138, v112, v113
	v_cvt_pk_bf16_f32 v139, v114, v115
	v_cvt_pk_bf16_f32 v140, v116, v117
	v_cvt_pk_bf16_f32 v141, v118, v119
	v_cvt_pk_bf16_f32 v142, v120, v121
	v_cvt_pk_bf16_f32 v143, v122, v123
	v_cvt_pk_bf16_f32 v52, v124, v125
	v_cvt_pk_bf16_f32 v53, v126, v127
	v_cvt_pk_bf16_f32 v54, v128, v129
	v_cvt_pk_bf16_f32 v55, v130, v131
	s_waitcnt lgkmcnt(15)
	s_nop 0
	v_mfma_f32_16x16x32_bf16 v[96:99], v[220:223], v[132:135], v[96:99]
	v_add_f32_e32 v100, v100, v101
	v_add_f32_e32 v102, v102, v103
	v_mfma_f32_16x16x32_bf16 v[84:87], v[220:223], v[140:143], v[84:87]
	v_add_f32_e32 v104, v104, v105
	v_add_f32_e32 v106, v106, v107
	v_mfma_f32_16x16x32_bf16 v[96:99], v[224:227], v[136:139], v[96:99]
	v_add_f32_e32 v108, v108, v109
	v_add_f32_e32 v110, v110, v111
	v_mfma_f32_16x16x32_bf16 v[84:87], v[224:227], v[52:55], v[84:87]
	v_add_f32_e32 v112, v112, v113
	v_add_f32_e32 v114, v114, v115
	ds_read_b64_tr_b16 v[220:221], v203 offset:21600
	ds_read_b64_tr_b16 v[222:223], v203 offset:24160
	v_mfma_f32_16x16x32_bf16 v[88:91], v[228:231], v[132:135], v[88:91]
	v_add_f32_e32 v100, v100, v102
	v_add_f32_e32 v104, v104, v106
	v_mfma_f32_16x16x32_bf16 v[76:79], v[228:231], v[140:143], v[76:79]
	v_add_f32_e32 v108, v108, v110
	v_add_f32_e32 v112, v112, v114
	v_mfma_f32_16x16x32_bf16 v[88:91], v[232:235], v[136:139], v[88:91]
	v_add_f32_e32 v100, v100, v104
	v_add_f32_e32 v108, v108, v112
	v_mfma_f32_16x16x32_bf16 v[76:79], v[232:235], v[52:55], v[76:79]
	v_add_f32_e32 v100, v100, v108
	v_add_f32_e32 v165, v165, v100
	s_waitcnt lgkmcnt(0)
	s_nop 0
	v_mfma_f32_16x16x32_bf16 v[92:95], v[236:239], v[132:135], v[92:95]
	v_add_f32_e32 v116, v116, v117
	v_add_f32_e32 v118, v118, v119
	v_mfma_f32_16x16x32_bf16 v[80:83], v[236:239], v[140:143], v[80:83]
	v_add_f32_e32 v120, v120, v121
	v_add_f32_e32 v122, v122, v123
	v_mfma_f32_16x16x32_bf16 v[92:95], v[240:243], v[136:139], v[92:95]
	v_add_f32_e32 v124, v124, v125
	v_add_f32_e32 v126, v126, v127
	v_mfma_f32_16x16x32_bf16 v[80:83], v[240:243], v[52:55], v[80:83]
	v_add_f32_e32 v128, v128, v129
	v_add_f32_e32 v130, v130, v131
	v_mfma_f32_16x16x32_bf16 v[48:51], v[244:247], v[132:135], v[48:51]
	v_add_f32_e32 v116, v116, v118
	v_add_f32_e32 v120, v120, v122
	v_mfma_f32_16x16x32_bf16 v[56:59], v[244:247], v[140:143], v[56:59]
	v_add_f32_e32 v124, v124, v126
	v_add_f32_e32 v128, v128, v130
	v_mfma_f32_16x16x32_bf16 v[48:51], v[220:223], v[136:139], v[48:51]
	v_add_f32_e32 v116, v116, v120
	v_add_f32_e32 v124, v124, v128
	v_mfma_f32_16x16x32_bf16 v[56:59], v[220:223], v[52:55], v[56:59]
	v_add_f32_e32 v116, v116, v124
	v_add_f32_e32 v164, v164, v116
	s_add_i32 s32, s49, 1
	s_cmp_eq_u32 s32, s9
	s_cbranch_scc1 .Lmla_mask4

; #define LAS __attribute__((address_space(3)))
; template <int I0, int NQ, int VO> __device__ __forceinline__ void tile_y(LAS unsigned char* lds, float (&l)[2], f32x4 (&o)[2][4], f32x4 (&s)[2][4], int fr, int fq) {
;     bf16x8 pb[NQ][2];
; #pragma unroll
;     for (int q = 0; q < NQ; ++q) {
;         f32x4 (&sq)[4] = s[I0 + q];
;         f32x2_t rs2 = {0.f, 0.f};
; #pragma unroll
;         for (int ss = 0; ss < 4; ++ss) {
; #pragma unroll
;             for (int i = 0; i < 4; ++i) sq[ss][i] = __builtin_amdgcn_exp2f(sq[ss][i]);
;             rs2 += (f32x2_t){sq[ss][0], sq[ss][1]}; rs2 += (f32x2_t){sq[ss][2], sq[ss][3]};
;         }
;         l[I0 + q] += rs2.x + rs2.y;
; #pragma unroll
;         for (int j = 0; j < 2; ++j) {
;             const v4u w = (v4u){cvtpk(sq[2 * j][0], sq[2 * j][1]), cvtpk(sq[2 * j][2], sq[2 * j][3]), cvtpk(sq[2 * j + 1][0], sq[2 * j + 1][1]), cvtpk(sq[2 * j + 1][2], sq[2 * j + 1][3])};
;             pb[q][j] = __builtin_bit_cast(bf16x8, w);
;         }
;     }
; #pragma unroll
;     for (int dt = 0; dt < 4; ++dt)
; #pragma unroll
;         for (int j = 0; j < 2; ++j) {
;             LAS unsigned char* vp = lds + VO + ((32 * j + 4 * fq + (fr >> 2)) * VSTR + 16 * dt + 4 * (fr & 3)) * 2;
;             const s16x4 lo = __builtin_bit_cast(s16x4, __builtin_amdgcn_ds_read_tr16_b64_v4i16((LAS v4i16_t*)vp));
;             const s16x4 hi = __builtin_bit_cast(s16x4, __builtin_amdgcn_ds_read_tr16_b64_v4i16((LAS v4i16_t*)(vp + 16 * VSTR * 2)));
;             const bf16x8 vf = (bf16x8){lo[0], lo[1], lo[2], lo[3], hi[0], hi[1], hi[2], hi[3]};
; #pragma unroll
;             for (int q = 0; q < NQ; ++q) o[I0 + q][dt] = __builtin_amdgcn_mfma_f32_16x16x32_bf16(vf, pb[q][j], o[I0 + q][dt], 0, 0, 0);
;         }
; }
; template <int DQK> __device__ __forceinline__ void x1_tile(LAS unsigned char* lds, const bf16x8 (&qf)[2][DQK / 32], const float (&m)[2], f32x4 (&s)[2][4], int fr, int fq) {
;     constexpr int NKS = DQK / 32;
; #pragma unroll
;     for (int q = 0; q < 2; ++q) { const float c = (m[q] > -1e29f) ? -m[q] : 0.f;
; #pragma unroll
;         for (int ss = 0; ss < 4; ++ss) s[q][ss] = (f32x4){c, c, c, c}; }
; #pragma unroll
;     for (int ss = 0; ss < 4; ++ss)
; #pragma unroll
;         for (int ks = 0; ks < NKS; ++ks) {
;             const bf16x8 kf = *(const LAS bf16x8*)(lds + k_off<DQK>(16 * ss + fr, 4 * ks + fq));
; #pragma unroll
.Lmla_nostage5:
	s_cmp_ge_u32 s49, s9
	s_cbranch_scc1 .Lmla_tail5
	ds_read_b64_tr_b16 v[220:221], v203 offset:43008
	ds_read_b64_tr_b16 v[222:223], v203 offset:45568
	ds_read_b64_tr_b16 v[224:225], v203 offset:48128
	ds_read_b64_tr_b16 v[226:227], v203 offset:50688
	ds_read_b64_tr_b16 v[228:229], v203 offset:43040
	ds_read_b64_tr_b16 v[230:231], v203 offset:45600
	ds_read_b64_tr_b16 v[232:233], v203 offset:48160
	ds_read_b64_tr_b16 v[234:235], v203 offset:50720
	ds_read_b128 v[236:239], v199
	ds_read_b128 v[240:243], v201
	ds_read_b128 v[244:247], v210
	s_waitcnt lgkmcnt(2)
	v_exp_f32_e32 v24, v24
	v_mfma_f32_16x16x32_bf16 v[100:103], v[236:239], v[0:3], v[204:207]
	v_exp_f32_e64 v25, v25
	v_mfma_f32_16x16x32_bf16 v[116:119], v[236:239], v[12:15], v[252:255]
	ds_read_b128 v[236:239], v199 offset:4096
	s_waitcnt lgkmcnt(2)
	v_exp_f32_e32 v26, v26
	v_mfma_f32_16x16x32_bf16 v[100:103], v[240:243], v[4:7], v[100:103]
	v_exp_f32_e64 v27, v27
	v_mfma_f32_16x16x32_bf16 v[116:119], v[240:243], v[16:19], v[116:119]
	ds_read_b128 v[240:243], v201 offset:4096
	s_waitcnt lgkmcnt(2)
	v_exp_f32_e32 v28, v28
	v_mfma_f32_16x16x32_bf16 v[100:103], v[244:247], v[8:11], v[100:103]
	v_exp_f32_e64 v29, v29
	v_mfma_f32_16x16x32_bf16 v[116:119], v[244:247], v[20:23], v[116:119]
	ds_read_b128 v[244:247], v210 offset:4096
	s_waitcnt lgkmcnt(2)
	v_exp_f32_e32 v30, v30
	v_mfma_f32_16x16x32_bf16 v[104:107], v[236:239], v[0:3], v[204:207]
	v_exp_f32_e64 v31, v31
	v_mfma_f32_16x16x32_bf16 v[120:123], v[236:239], v[12:15], v[252:255]
	ds_read_b128 v[236:239], v199 offset:8192
	s_waitcnt lgkmcnt(2)
	v_exp_f32_e32 v32, v32
	v_mfma_f32_16x16x32_bf16 v[104:107], v[240:243], v[4:7], v[104:107]
	v_exp_f32_e64 v33, v33
	v_mfma_f32_16x16x32_bf16 v[120:123], v[240:243], v[16:19], v[120:123]
	ds_read_b128 v[240:243], v201 offset:8192
	s_waitcnt lgkmcnt(2)
	v_exp_f32_e32 v34, v34
	v_mfma_f32_16x16x32_bf16 v[104:107], v[244:247], v[8:11], v[104:107]
	v_exp_f32_e64 v35, v35
	v_mfma_f32_16x16x32_bf16 v[120:123], v[244:247], v[20:23], v[120:123]
	ds_read_b128 v[244:247], v210 offset:8192
	s_waitcnt lgkmcnt(2)
	v_exp_f32_e32 v36, v36
	v_mfma_f32_16x16x32_bf16 v[108:111], v[236:239], v[0:3], v[204:207]
	v_exp_f32_e64 v37, v37
	v_mfma_f32_16x16x32_bf16 v[124:127], v[236:239], v[12:15], v[252:255]
	ds_read_b128 v[236:239], v199 offset:12288
	s_waitcnt lgkmcnt(2)
	v_exp_f32_e32 v38, v38
	v_mfma_f32_16x16x32_bf16 v[108:111], v[240:243], v[4:7], v[108:111]
	v_exp_f32_e64 v39, v39
	v_mfma_f32_16x16x32_bf16 v[124:127], v[240:243], v[16:19], v[124:127]
	ds_read_b128 v[240:243], v201 offset:12288
	s_waitcnt lgkmcnt(2)
	v_exp_f32_e32 v40, v40
	v_mfma_f32_16x16x32_bf16 v[108:111], v[244:247], v[8:11], v[108:111]
	v_exp_f32_e64 v41, v41
	v_mfma_f32_16x16x32_bf16 v[124:127], v[244:247], v[20:23], v[124:127]
	ds_read_b128 v[244:247], v210 offset:12288
	s_waitcnt lgkmcnt(2)
	v_exp_f32_e32 v42, v42
	v_mfma_f32_16x16x32_bf16 v[112:115], v[236:239], v[0:3], v[204:207]
	v_exp_f32_e64 v43, v43
	v_mfma_f32_16x16x32_bf16 v[128:131], v[236:239], v[12:15], v[252:255]
	ds_read_b64_tr_b16 v[236:237], v203 offset:43072
	ds_read_b64_tr_b16 v[238:239], v203 offset:45632
	s_waitcnt lgkmcnt(3)
	v_exp_f32_e32 v44, v44
	v_mfma_f32_16x16x32_bf16 v[112:115], v[240:243], v[4:7], v[112:115]
	v_exp_f32_e64 v45, v45
	v_mfma_f32_16x16x32_bf16 v[128:131], v[240:243], v[16:19], v[128:131]
	ds_read_b64_tr_b16 v[240:241], v203 offset:48192
	ds_read_b64_tr_b16 v[242:243], v203 offset:50752
	s_waitcnt lgkmcnt(4)
	v_exp_f32_e32 v46, v46
	v_mfma_f32_16x16x32_bf16 v[112:115], v[244:247], v[8:11], v[112:115]
	v_exp_f32_e64 v47, v47
	v_mfma_f32_16x16x32_bf16 v[128:131], v[244:247], v[20:23], v[128:131]
	ds_read_b64_tr_b16 v[244:245], v203 offset:43104
	ds_read_b64_tr_b16 v[246:247], v203 offset:45664
	v_exp_f32_e32 v212, v212
	v_exp_f32_e32 v213, v213
	v_exp_f32_e32 v214, v214
	v_exp_f32_e32 v215, v215
	v_exp_f32_e32 v216, v216
	v_exp_f32_e32 v217, v217
	v_exp_f32_e32 v218, v218
	v_exp_f32_e32 v219, v219
	v_cvt_pk_bf16_f32 v132, v24, v25
	v_cvt_pk_bf16_f32 v133, v26, v27
	v_cvt_pk_bf16_f32 v134, v28, v29
	v_cvt_pk_bf16_f32 v135, v30, v31
	v_cvt_pk_bf16_f32 v136, v32, v33
	v_cvt_pk_bf16_f32 v137, v34, v35
	v_cvt_pk_bf16_f32 v138, v36, v37
	v_cvt_pk_bf16_f32 v139, v38, v39
	v_cvt_pk_bf16_f32 v140, v40, v41
	v_cvt_pk_bf16_f32 v141, v42, v43
	v_cvt_pk_bf16_f32 v142, v44, v45
	v_cvt_pk_bf16_f32 v143, v46, v47
	v_cvt_pk_bf16_f32 v52, v212, v213
	v_cvt_pk_bf16_f32 v53, v214, v215
	v_cvt_pk_bf16_f32 v54, v216, v217
	v_cvt_pk_bf16_f32 v55, v218, v219
	s_waitcnt lgkmcnt(15)
	s_nop 0
	v_mfma_f32_16x16x32_bf16 v[96:99], v[220:223], v[132:135], v[96:99]
	v_add_f32_e32 v24, v24, v25
	v_add_f32_e32 v26, v26, v27
	v_mfma_f32_16x16x32_bf16 v[84:87], v[220:223], v[140:143], v[84:87]
	v_add_f32_e32 v28, v28, v29
	v_add_f32_e32 v30, v30, v31
	v_mfma_f32_16x16x32_bf16 v[96:99], v[224:227], v[136:139], v[96:99]
	v_add_f32_e32 v32, v32, v33
	v_add_f32_e32 v34, v34, v35
	v_mfma_f32_16x16x32_bf16 v[84:87], v[224:227], v[52:55], v[84:87]
	v_add_f32_e32 v36, v36, v37
	v_add_f32_e32 v38, v38, v39
	ds_read_b64_tr_b16 v[220:221], v203 offset:48224
	ds_read_b64_tr_b16 v[222:223], v203 offset:50784
	v_mfma_f32_16x16x32_bf16 v[88:91], v[228:231], v[132:135], v[88:91]
	v_add_f32_e32 v24, v24, v26
	v_add_f32_e32 v28, v28, v30
	v_mfma_f32_16x16x32_bf16 v[76:79], v[228:231], v[140:143], v[76:79]
	v_add_f32_e32 v32, v32, v34
	v_add_f32_e32 v36, v36, v38
	v_mfma_f32_16x16x32_bf16 v[88:91], v[232:235], v[136:139], v[88:91]
	v_add_f32_e32 v24, v24, v28
	v_add_f32_e32 v32, v32, v36
	v_mfma_f32_16x16x32_bf16 v[76:79], v[232:235], v[52:55], v[76:79]
	v_add_f32_e32 v24, v24, v32
	v_add_f32_e32 v165, v165, v24
	s_waitcnt lgkmcnt(0)
	s_nop 0
	v_mfma_f32_16x16x32_bf16 v[92:95], v[236:239], v[132:135], v[92:95]
	v_add_f32_e32 v40, v40, v41
	v_add_f32_e32 v42, v42, v43
	v_mfma_f32_16x16x32_bf16 v[80:83], v[236:239], v[140:143], v[80:83]
	v_add_f32_e32 v44, v44, v45
	v_add_f32_e32 v46, v46, v47
	v_mfma_f32_16x16x32_bf16 v[92:95], v[240:243], v[136:139], v[92:95]
	v_add_f32_e32 v212, v212, v213
	v_add_f32_e32 v214, v214, v215
	v_mfma_f32_16x16x32_bf16 v[80:83], v[240:243], v[52:55], v[80:83]
	v_add_f32_e32 v216, v216, v217
	v_add_f32_e32 v218, v218, v219
	v_mfma_f32_16x16x32_bf16 v[48:51], v[244:247], v[132:135], v[48:51]
	v_add_f32_e32 v40, v40, v42
	v_add_f32_e32 v44, v44, v46
	v_mfma_f32_16x16x32_bf16 v[56:59], v[244:247], v[140:143], v[56:59]
	v_add_f32_e32 v212, v212, v214
	v_add_f32_e32 v216, v216, v218
	v_mfma_f32_16x16x32_bf16 v[48:51], v[220:223], v[136:139], v[48:51]
	v_add_f32_e32 v40, v40, v44
	v_add_f32_e32 v212, v212, v216
	v_mfma_f32_16x16x32_bf16 v[56:59], v[220:223], v[52:55], v[56:59]
	v_add_f32_e32 v40, v40, v212
	v_add_f32_e32 v164, v164, v40
	s_add_i32 s32, s49, 1
	s_cmp_eq_u32 s32, s9
	s_cbranch_scc1 .Lmla_mask5
